# deferred-conversion throttle raised to s_sleep 110 per item
# speedup vs baseline: 1.0110x; 1.0006x over previous
; __device__ void ph_prep(const P& p, float* lds) {
;     ...
;     } else if (it < NTR + NCV) {
;       int j = it - NTR;
;       if (j < 16) conv_chunk4(p.keys1, p_K1b, (size_t)j * 8192);
;       else if ((j -= 16) < 16) conv_chunk4(p.keys2, p_K2b, (size_t)j * 8192);
;       else if ((j -= 16) < 2048) conv_table_chunk4(p.pu, p_U8, (size_t)j * 8192, SU);
;       else if ((j -= 2048) < 2048) conv_table_chunk4(p.pv, p_V8, (size_t)j * 8192, SV);
;       else if ((j -= 2048) < 1024) conv_chunk4(p.p_p, p_Pb, (size_t)j * 8192);
;       else { j -= 1024; conv_chunk4(p.p_s, p_Pb + (size_t)TP * 256, (size_t)j * 8192); }
.Ldef_next:
	s_sleep 110
	s_add_u32 s50, s50, s51
	s_branch .Ldef_loop
